# A/B: hipcc per-segment s_setprio flips deleted inside the attention tile loop (everything else as the previous best)
# baseline (speedup 1.0000x reference)
; #define SBAR() __builtin_amdgcn_sched_barrier(0)
; __device__ __forceinline__ void finishSM(f32x16& p0, f32x16& p1, float alpha, float& l_reg, bf16x8& pa0, bf16x8& pa1, bf16x8& pa2, bf16x8& pa3) {
; #pragma unroll
;     for (int r = 0; r < 16; ++r) p1[r] = __builtin_amdgcn_exp2f(p1[r]);
;     float ps = 0;
; #pragma unroll
;     for (int r = 0; r < 16; ++r) ps += p0[r];
; #pragma unroll
;     for (int r = 0; r < 16; ++r) ps += p1[r];
;     { auto rr = __builtin_amdgcn_permlane32_swap(__float_as_uint(ps), __float_as_uint(ps), false, false);
;       ps = __uint_as_float(rr[0]) + __uint_as_float(rr[1]); }
;     l_reg = l_reg * alpha + ps;
;     ...
;     PK4(p0, 0, pa0); PK4(p0, 8, pa1); PK4(p1, 0, pa2); PK4(p1, 8, pa3);
;     ...
; }
; __device__ __forceinline__ void qkt(f32x16& p0, f32x16& p1, const char* Kn, const bf16x8* qr, int r32, int hi) {
;     const char* Kr = Kn + KR_OFF;
;     p0 = f32x16{}; p1 = f32x16{};
;     __builtin_amdgcn_s_setprio(1);
; #pragma unroll
;     for (int d0 = 0; d0 < 8; ++d0) { const int cb = (d0 * 16 + hi * 8) * 2;
;         const bf16x8 b0 = *reinterpret_cast<const bf16x8*>(Kn + KNSWZ(r32, cb));
;         const bf16x8 b1 = *reinterpret_cast<const bf16x8*>(Kn + KNSWZ(32 + r32, cb));
;         p0 = __builtin_amdgcn_mfma_f32_32x32x16_bf16(b0, qr[d0], p0, 0, 0, 0);
;         p1 = __builtin_amdgcn_mfma_f32_32x32x16_bf16(b1, qr[d0], p1, 0, 0, 0); }
; #pragma unroll
;     for (int d0 = 0; d0 < 4; ++d0) { const int cb = (d0 * 16 + hi * 8) * 2;
;         const bf16x8 b0 = *reinterpret_cast<const bf16x8*>(Kr + KRSWZ(r32, cb));
;         const bf16x8 b1 = *reinterpret_cast<const bf16x8*>(Kr + KRSWZ(32 + r32, cb));
;         p0 = __builtin_amdgcn_mfma_f32_32x32x16_bf16(b0, qr[8 + d0], p0, 0, 0, 0);
;         p1 = __builtin_amdgcn_mfma_f32_32x32x16_bf16(b1, qr[8 + d0], p1, 0, 0, 0); }
; }
; template <int D0> __device__ __forceinline__ void pv_one(f32x16& od, int vb, bf16x8 pa0, bf16x8 pa1, bf16x8 pa2, bf16x8 pa3) {
;     const s16x4 l0 = tr_read<v_rd_off(D0, 0, 0)>(vb), h0 = tr_read<v_rd_off(D0, 0, 1)>(vb), l1 = tr_read<v_rd_off(D0, 1, 0)>(vb), h1 = tr_read<v_rd_off(D0, 1, 1)>(vb);
;     const s16x4 l2 = tr_read<v_rd_off(D0, 2, 0)>(vb), h2 = tr_read<v_rd_off(D0, 2, 1)>(vb), l3 = tr_read<v_rd_off(D0, 3, 0)>(vb), h3 = tr_read<v_rd_off(D0, 3, 1)>(vb);
;     asm volatile("s_waitcnt lgkmcnt(0)" ::: "memory"); SBAR();
.LBB0_216:
	s_mul_i32 s0, s9, 0x6000
	s_add_i32 s14, s0, 0
	s_lshl_b32 s13, s9, 14
	s_add_i32 s16, s14, s6
	s_add_i32 s17, s7, s13
	s_add_i32 s18, s14, s8
	s_mov_b32 s13, s10
	s_mov_b32 s10, s15
	s_mul_i32 s0, s13, 0x6000
	s_add_i32 s0, s0, 0
	v_add_u32_e32 v84, s0, v207
	ds_read_b128 v[80:83], v84
	ds_read_b128 v[84:87], v84 offset:8192
	v_add_u32_e32 v168, s0, v210
	ds_read_b128 v[196:199], v168
	ds_read_b128 v[168:171], v168 offset:8192
	v_add_u32_e32 v184, s0, v218
	s_waitcnt lgkmcnt(0)
	v_mfma_f32_32x32x16_bf16 v[96:111], v[80:83], v[156:159], 0
	v_mfma_f32_32x32x16_bf16 v[80:95], v[84:87], v[156:159], 0
	v_mfma_f32_32x32x16_bf16 v[96:111], v[196:199], v[152:155], v[96:111]
	v_mfma_f32_32x32x16_bf16 v[80:95], v[168:171], v[152:155], v[80:95]
	ds_read_b128 v[168:171], v184
	ds_read_b128 v[196:199], v184 offset:8192
	v_add_u32_e32 v184, s0, v221
	s_mov_b32 m0, s16
	s_add_u32 s100, s72, 0x26500000
	s_addc_u32 s101, s73, 0
	global_load_lds_dwordx4 v178, s[100:101]
	s_waitcnt lgkmcnt(0)
	v_mfma_f32_32x32x16_bf16 v[96:111], v[168:171], v[148:151], v[96:111]
	v_mfma_f32_32x32x16_bf16 v[80:95], v[196:199], v[148:151], v[80:95]
	ds_read_b128 v[168:171], v184
	ds_read_b128 v[196:199], v184 offset:8192
	v_add_u32_e32 v184, s0, v222
	s_waitcnt lgkmcnt(0)
	v_mfma_f32_32x32x16_bf16 v[96:111], v[168:171], v[144:147], v[96:111]
	v_mfma_f32_32x32x16_bf16 v[80:95], v[196:199], v[144:147], v[80:95]
	ds_read_b128 v[168:171], v184
	ds_read_b128 v[196:199], v184 offset:8192
	v_add_u32_e32 v184, s0, v223
	s_add_i32 m0, s16, 0x400
	s_nop 0
	global_load_lds_dwordx4 v180, s[100:101]
	s_waitcnt lgkmcnt(0)
	v_mfma_f32_32x32x16_bf16 v[96:111], v[168:171], v[140:143], v[96:111]
	v_mfma_f32_32x32x16_bf16 v[80:95], v[196:199], v[140:143], v[80:95]
	ds_read_b128 v[168:171], v184
	ds_read_b128 v[196:199], v184 offset:8192
	v_add_u32_e32 v184, s0, v224
	v_exp_f32_e32 v233, v73
	s_waitcnt lgkmcnt(0)
	v_mfma_f32_32x32x16_bf16 v[96:111], v[168:171], v[136:139], v[96:111]
	v_mfma_f32_32x32x16_bf16 v[80:95], v[196:199], v[136:139], v[80:95]
	ds_read_b128 v[168:171], v184
	ds_read_b128 v[196:199], v184 offset:8192
	v_add_u32_e32 v184, s0, v225
	s_mov_b32 m0, s17
	s_add_u32 s100, s72, 0x26500100
	s_addc_u32 s101, s73, 0
	global_load_lds_dwordx4 v176, s[100:101]
	v_exp_f32_e32 v250, v74
	s_waitcnt lgkmcnt(0)
	v_mfma_f32_32x32x16_bf16 v[96:111], v[168:171], v[132:135], v[96:111]
	v_mfma_f32_32x32x16_bf16 v[80:95], v[196:199], v[132:135], v[80:95]
	ds_read_b128 v[168:171], v184
	ds_read_b128 v[196:199], v184 offset:8192
	v_add_u32_e32 v184, s0, v226
	v_exp_f32_e32 v200, v75
	s_waitcnt lgkmcnt(0)
	v_mfma_f32_32x32x16_bf16 v[96:111], v[168:171], v[128:131], v[96:111]
	v_mfma_f32_32x32x16_bf16 v[80:95], v[196:199], v[128:131], v[80:95]
	ds_read_b128 v[168:171], v184 offset:16384
	ds_read_b128 v[196:199], v184 offset:20480
	v_add_u32_e32 v184, s0, v227
	s_add_i32 m0, s17, 0x400
	s_add_u32 s100, s72, 0x26500180
	s_addc_u32 s101, s73, 0
	global_load_lds_dwordx4 v176, s[100:101]
	v_exp_f32_e32 v195, v76
	s_waitcnt lgkmcnt(0)
	v_mfma_f32_32x32x16_bf16 v[96:111], v[168:171], v[124:127], v[96:111]
	v_mfma_f32_32x32x16_bf16 v[80:95], v[196:199], v[124:127], v[80:95]
	ds_read_b128 v[168:171], v184 offset:16384
	ds_read_b128 v[196:199], v184 offset:20480
	v_add_u32_e32 v184, s0, v228
	v_exp_f32_e32 v172, v77
	s_waitcnt lgkmcnt(0)
	v_mfma_f32_32x32x16_bf16 v[96:111], v[168:171], v[120:123], v[96:111]
	v_mfma_f32_32x32x16_bf16 v[80:95], v[196:199], v[120:123], v[80:95]
	ds_read_b128 v[168:171], v184 offset:16384
	ds_read_b128 v[196:199], v184 offset:20480
	v_add_u32_e32 v184, s0, v229
	s_add_i32 m0, s18, 0x4000
	s_add_u32 s100, s72, 0x21204000
	s_addc_u32 s101, s73, 0
	global_load_lds_dwordx4 v174, s[100:101]
	v_exp_f32_e32 v173, v78
	s_waitcnt lgkmcnt(0)
	v_mfma_f32_32x32x16_bf16 v[96:111], v[168:171], v[116:119], v[96:111]
	v_mfma_f32_32x32x16_bf16 v[80:95], v[196:199], v[116:119], v[80:95]
	ds_read_b128 v[168:171], v184 offset:16384
	ds_read_b128 v[196:199], v184 offset:20480
	v_exp_f32_e32 v184, v68
	v_exp_f32_e32 v79, v79
	s_waitcnt lgkmcnt(0)
	v_mfma_f32_32x32x16_bf16 v[96:111], v[168:171], v[112:115], v[96:111]
	v_exp_f32_e32 v168, v64
	v_add_f32_e32 v64, 0, v247
	v_add_f32_e32 v64, v249, v64
	v_add_f32_e32 v64, v245, v64
	v_add_f32_e32 v64, v248, v64
	v_add_f32_e32 v64, v244, v64
	v_add_f32_e32 v64, v246, v64
	v_add_f32_e32 v64, v242, v64
	v_add_f32_e32 v64, v243, v64
	v_add_f32_e32 v64, v239, v64
	v_add_f32_e32 v64, v241, v64
	v_add_f32_e32 v64, v238, v64
	v_add_f32_e32 v64, v240, v64
	v_add_f32_e32 v64, v235, v64
	v_exp_f32_e32 v169, v65
	v_add_f32_e32 v64, v237, v64
	v_exp_f32_e32 v170, v66
	v_add_f32_e32 v64, v234, v64
	v_exp_f32_e32 v171, v67
	v_add_f32_e32 v64, v236, v64
	v_add_f32_e32 v64, v168, v64
	v_mfma_f32_32x32x16_bf16 v[80:95], v[196:199], v[112:115], v[80:95]
	v_exp_f32_e32 v196, v69
	v_add_f32_e32 v64, v169, v64
	v_exp_f32_e32 v197, v70
	v_add_f32_e32 v64, v170, v64
	v_exp_f32_e32 v198, v71
	v_add_f32_e32 v64, v171, v64
	v_exp_f32_e32 v199, v72
	v_add_f32_e32 v64, v184, v64
	v_add_f32_e32 v64, v196, v64
	v_add_f32_e32 v64, v197, v64
	v_add_f32_e32 v64, v198, v64
	v_add_f32_e32 v64, v199, v64
	v_add_f32_e32 v64, v233, v64
	v_add_f32_e32 v64, v250, v64
	v_add_f32_e32 v64, v200, v64
	v_add_f32_e32 v64, v195, v64
	v_add_f32_e32 v64, v172, v64
	v_add_f32_e32 v64, v173, v64
	v_add_f32_e32 v231, v79, v64
	v_mov_b32_e32 v232, v231
	v_cvt_pk_bf16_f32 v64, v247, v249
	v_cvt_pk_bf16_f32 v65, v245, v248
	v_cvt_pk_bf16_f32 v66, v244, v246
	s_nop 1
	v_permlane32_swap_b32_e32 v231, v232
	v_cvt_pk_bf16_f32 v67, v242, v243
	v_permlane32_swap_b32_e32 v64, v66
	v_cvt_pk_bf16_f32 v68, v239, v241
	v_cvt_pk_bf16_f32 v69, v238, v240
	v_cvt_pk_bf16_f32 v70, v235, v237
	v_cvt_pk_bf16_f32 v71, v234, v236
	v_cvt_pk_bf16_f32 v72, v168, v169
	v_cvt_pk_bf16_f32 v73, v170, v171
	v_cvt_pk_bf16_f32 v74, v184, v196
	v_cvt_pk_bf16_f32 v75, v197, v198
	v_cvt_pk_bf16_f32 v76, v199, v233
	v_cvt_pk_bf16_f32 v77, v250, v200
	v_cvt_pk_bf16_f32 v78, v195, v172
	v_cvt_pk_bf16_f32 v79, v173, v79
	s_lshl_b32 s15, s15, 14
	v_add_u32_e32 v172, s15, v205
	ds_read_b64_tr_b16 v[168:169], v172 offset:0
	ds_read_b64_tr_b16 v[170:171], v172 offset:0x800
	ds_read_b64_tr_b16 v[196:197], v172 offset:0x1000
	ds_read_b64_tr_b16 v[198:199], v172 offset:0x1800
	ds_read_b64_tr_b16 v[234:235], v172 offset:0x2000
	ds_read_b64_tr_b16 v[236:237], v172 offset:0x2800
	ds_read_b64_tr_b16 v[238:239], v172 offset:0x3000
	ds_read_b64_tr_b16 v[240:241], v172 offset:0x3800
	v_permlane32_swap_b32_e32 v65, v67
	v_permlane32_swap_b32_e32 v68, v70
	v_permlane32_swap_b32_e32 v69, v71
	v_permlane32_swap_b32_e32 v72, v74
	v_permlane32_swap_b32_e32 v73, v75
	v_permlane32_swap_b32_e32 v76, v78
	v_permlane32_swap_b32_e32 v77, v79
	s_waitcnt lgkmcnt(0)
; #define SBAR() __builtin_amdgcn_sched_barrier(0)
; __device__ __forceinline__ void qkt(f32x16& p0, f32x16& p1, const char* Kn, const bf16x8* qr, int r32, int hi) {
;     const char* Kr = Kn + KR_OFF;
;     p0 = f32x16{}; p1 = f32x16{};
;     __builtin_amdgcn_s_setprio(1);
; #pragma unroll
;     for (int d0 = 0; d0 < 8; ++d0) { const int cb = (d0 * 16 + hi * 8) * 2;
;         const bf16x8 b0 = *reinterpret_cast<const bf16x8*>(Kn + KNSWZ(r32, cb));
;         const bf16x8 b1 = *reinterpret_cast<const bf16x8*>(Kn + KNSWZ(32 + r32, cb));
;         p0 = __builtin_amdgcn_mfma_f32_32x32x16_bf16(b0, qr[d0], p0, 0, 0, 0);
;         p1 = __builtin_amdgcn_mfma_f32_32x32x16_bf16(b1, qr[d0], p1, 0, 0, 0); }
; #pragma unroll
;     for (int d0 = 0; d0 < 4; ++d0) { const int cb = (d0 * 16 + hi * 8) * 2;
;         const bf16x8 b0 = *reinterpret_cast<const bf16x8*>(Kr + KRSWZ(r32, cb));
;         const bf16x8 b1 = *reinterpret_cast<const bf16x8*>(Kr + KRSWZ(32 + r32, cb));
;         p0 = __builtin_amdgcn_mfma_f32_32x32x16_bf16(b0, qr[8 + d0], p0, 0, 0, 0);
;         p1 = __builtin_amdgcn_mfma_f32_32x32x16_bf16(b1, qr[8 + d0], p1, 0, 0, 0); }
; }
; __device__ __forceinline__ int v_st(int k, int c) { const int kk = (k & ~0xC) | ((k & 4) << 1) | ((k & 8) >> 1); return ((kk >> 3) * 4 + (c >> 5)) * 512 + ((kk & 7) * 32 + (c & 31)) * 2; }
; __device__ __forceinline__ int v_rd_base(int lane) { return ((lane & 3) << 3) | (((lane >> 2) & 3) << 6) | (((lane >> 4) & 1) << 5) | (((lane >> 5) & 1) << 8); }
; template <int OFF> __device__ __forceinline__ s16x4 tr_read(int vb) {
;     s16x4 r; asm volatile("ds_read_b64_tr_b16 %0, %1 offset:%2" : "=&v"(r) : "v"(vb), "i"(OFF) : "memory"); return r;
; }
; template <int D0> __device__ __forceinline__ void pv_one(f32x16& od, int vb, bf16x8 pa0, bf16x8 pa1, bf16x8 pa2, bf16x8 pa3) {
;     const s16x4 l0 = tr_read<v_rd_off(D0, 0, 0)>(vb), h0 = tr_read<v_rd_off(D0, 0, 1)>(vb), l1 = tr_read<v_rd_off(D0, 1, 0)>(vb), h1 = tr_read<v_rd_off(D0, 1, 1)>(vb);
;     const s16x4 l2 = tr_read<v_rd_off(D0, 2, 0)>(vb), h2 = tr_read<v_rd_off(D0, 2, 1)>(vb), l3 = tr_read<v_rd_off(D0, 3, 0)>(vb), h3 = tr_read<v_rd_off(D0, 3, 1)>(vb);
;     asm volatile("s_waitcnt lgkmcnt(0)" ::: "memory"); SBAR();
;     ...
;     od = __builtin_amdgcn_mfma_f32_32x32x16_bf16(pa0, PK(l0, h0), od, 0, 0, 0);
;     od = __builtin_amdgcn_mfma_f32_32x32x16_bf16(pa1, PK(l1, h1), od, 0, 0, 0);
	s_nop 0
	v_mfma_f32_32x32x16_bf16 v[0:15], v[64:67], v[168:171], v[0:15]
	ds_read_b64_tr_b16 v[168:169], v172 offset:0x200
	ds_read_b64_tr_b16 v[170:171], v172 offset:0xa00
	v_mfma_f32_32x32x16_bf16 v[0:15], v[68:71], v[196:199], v[0:15]
	ds_read_b64_tr_b16 v[196:197], v172 offset:0x1200
	ds_read_b64_tr_b16 v[198:199], v172 offset:0x1a00
	v_mfma_f32_32x32x16_bf16 v[0:15], v[72:75], v[234:237], v[0:15]
	ds_read_b64_tr_b16 v[234:235], v172 offset:0x2200
	ds_read_b64_tr_b16 v[236:237], v172 offset:0x2a00
	v_mfma_f32_32x32x16_bf16 v[0:15], v[76:79], v[238:241], v[0:15]
	ds_read_b64_tr_b16 v[238:239], v172 offset:0x3200
	ds_read_b64_tr_b16 v[240:241], v172 offset:0x3a00
	s_waitcnt lgkmcnt(0)
	v_mfma_f32_32x32x16_bf16 v[48:63], v[64:67], v[168:171], v[48:63]
	ds_read_b64_tr_b16 v[168:169], v172 offset:0x400
	ds_read_b64_tr_b16 v[170:171], v172 offset:0xc00
	v_mfma_f32_32x32x16_bf16 v[48:63], v[68:71], v[196:199], v[48:63]
	ds_read_b64_tr_b16 v[196:197], v172 offset:0x1400
	ds_read_b64_tr_b16 v[198:199], v172 offset:0x1c00
	v_mfma_f32_32x32x16_bf16 v[48:63], v[72:75], v[234:237], v[48:63]
	ds_read_b64_tr_b16 v[234:235], v172 offset:0x2400
	ds_read_b64_tr_b16 v[236:237], v172 offset:0x2c00
	v_mfma_f32_32x32x16_bf16 v[48:63], v[76:79], v[238:241], v[48:63]
	ds_read_b64_tr_b16 v[238:239], v172 offset:0x3400
	ds_read_b64_tr_b16 v[240:241], v172 offset:0x3c00
	s_waitcnt lgkmcnt(0)
	v_mfma_f32_32x32x16_bf16 v[32:47], v[64:67], v[168:171], v[32:47]
	ds_read_b64_tr_b16 v[168:169], v172 offset:0x600
	ds_read_b64_tr_b16 v[170:171], v172 offset:0xe00
	v_mfma_f32_32x32x16_bf16 v[32:47], v[68:71], v[196:199], v[32:47]
	ds_read_b64_tr_b16 v[196:197], v172 offset:0x1600
	ds_read_b64_tr_b16 v[198:199], v172 offset:0x1e00
	v_mfma_f32_32x32x16_bf16 v[32:47], v[72:75], v[234:237], v[32:47]
	ds_read_b64_tr_b16 v[234:235], v172 offset:0x2600
	ds_read_b64_tr_b16 v[236:237], v172 offset:0x2e00
	v_mfma_f32_32x32x16_bf16 v[32:47], v[76:79], v[238:241], v[32:47]
	ds_read_b64_tr_b16 v[238:239], v172 offset:0x3600
	ds_read_b64_tr_b16 v[240:241], v172 offset:0x3e00
	s_waitcnt lgkmcnt(0)
	v_mfma_f32_32x32x16_bf16 v[16:31], v[64:67], v[168:171], v[16:31]
	v_max_f32_e32 v64, v97, v97
	v_max_f32_e32 v65, v96, v96
	v_max_f32_e32 v64, v65, v64
	v_max3_f32 v64, v64, v98, v99
	v_max3_f32 v64, v64, v100, v101
	v_max3_f32 v64, v64, v102, v103
	v_max3_f32 v64, v64, v104, v105
	v_mfma_f32_32x32x16_bf16 v[16:31], v[68:71], v[196:199], v[16:31]
	v_max3_f32 v64, v64, v106, v107
	v_max3_f32 v64, v64, v108, v109
	v_max3_f32 v64, v64, v110, v111
	v_max3_f32 v64, v64, v80, v81
	v_max3_f32 v64, v64, v82, v83
	v_max3_f32 v64, v64, v84, v85
	v_max3_f32 v64, v64, v86, v87
	v_mfma_f32_32x32x16_bf16 v[16:31], v[72:75], v[234:237], v[16:31]
	v_max3_f32 v64, v64, v88, v89
	v_max3_f32 v64, v64, v90, v91
	v_max3_f32 v64, v64, v92, v93
	v_max3_f32 v64, v64, v94, v95
	v_mov_b32_e32 v65, v64
	s_nop 1
	v_permlane32_swap_b32_e32 v64, v65
	v_max_f32_e32 v65, v65, v65
	v_max_f32_e32 v64, v64, v64
	v_mfma_f32_32x32x16_bf16 v[16:31], v[76:79], v[238:241], v[16:31]
	v_max_f32_e32 v64, v64, v65
	v_sub_f32_e32 v65, v64, v182
	s_mov_b32 s0, 0x41300000
	v_cmp_ge_f32_e32 vcc, s0, v65
	v_mov_b32_e32 v184, v182
	v_mov_b32_e32 v233, 1.0
	s_cmp_eq_u64 vcc, exec
	s_cbranch_scc0 .Latt_slow1
	s_cmp_lg_u32 s19, 0
	s_cbranch_scc0 .LBB0_228
.LBB0_221:
	v_exp_f32_e32 v182, v98
	v_exp_f32_e32 v172, v96
	v_exp_f32_e32 v173, v97
	v_exp_f32_e32 v195, v99
	v_exp_f32_e32 v196, v100
	v_exp_f32_e32 v197, v101
	v_exp_f32_e32 v198, v102
	v_exp_f32_e32 v199, v103
	v_exp_f32_e32 v200, v104
	v_exp_f32_e32 v234, v105
	v_exp_f32_e32 v235, v106
	v_exp_f32_e32 v236, v107
	v_exp_f32_e32 v237, v108
	v_exp_f32_e32 v238, v109
	v_exp_f32_e32 v239, v110
	v_exp_f32_e32 v240, v111
	v_add_u32_e32 v68, s14, v207
	v_add_u32_e32 v186, s14, v210
	s_mul_i32 s0, s10, 0x6000
	s_add_i32 s16, s0, 0
	s_add_i32 s17, s16, s6
	s_add_i32 s18, s16, s8
	s_waitcnt vmcnt(0) lgkmcnt(0)
	s_barrier
	s_add_i32 s15, s7, s15
	ds_read_b128 v[64:67], v68
	ds_read_b128 v[68:71], v68 offset:8192
	ds_read_b128 v[168:171], v186
	ds_read_b128 v[186:189], v186 offset:8192
	s_waitcnt lgkmcnt(0)
	v_mfma_f32_32x32x16_bf16 v[96:111], v[64:67], v[156:159], 0
	v_mfma_f32_32x32x16_bf16 v[64:79], v[68:71], v[156:159], 0
	v_mfma_f32_32x32x16_bf16 v[96:111], v[168:171], v[152:155], v[96:111]
	v_mfma_f32_32x32x16_bf16 v[64:79], v[186:189], v[152:155], v[64:79]
	v_add_u32_e32 v186, s14, v218
	ds_read_b128 v[168:171], v186
	ds_read_b128 v[186:189], v186 offset:8192
	s_mov_b32 m0, s17
	s_add_u32 s100, s72, 0x26580000
	s_addc_u32 s101, s73, 0
	global_load_lds_dwordx4 v178, s[100:101]
	s_waitcnt lgkmcnt(0)
	v_mfma_f32_32x32x16_bf16 v[96:111], v[168:171], v[148:151], v[96:111]
	v_mfma_f32_32x32x16_bf16 v[64:79], v[186:189], v[148:151], v[64:79]
	v_add_u32_e32 v186, s14, v221
	ds_read_b128 v[168:171], v186
	ds_read_b128 v[186:189], v186 offset:8192
	s_waitcnt lgkmcnt(0)
	v_mfma_f32_32x32x16_bf16 v[96:111], v[168:171], v[144:147], v[96:111]
	v_mfma_f32_32x32x16_bf16 v[64:79], v[186:189], v[144:147], v[64:79]
	v_add_u32_e32 v186, s14, v222
	ds_read_b128 v[168:171], v186
	ds_read_b128 v[186:189], v186 offset:8192
	s_add_i32 m0, s17, 0x400
	s_nop 0
	global_load_lds_dwordx4 v180, s[100:101]
	v_exp_f32_e32 v190, v88
	s_waitcnt lgkmcnt(0)
	v_mfma_f32_32x32x16_bf16 v[96:111], v[168:171], v[140:143], v[96:111]
	v_mfma_f32_32x32x16_bf16 v[64:79], v[186:189], v[140:143], v[64:79]
	v_add_u32_e32 v186, s14, v223
	ds_read_b128 v[168:171], v186
	ds_read_b128 v[186:189], v186 offset:8192
	v_exp_f32_e32 v191, v89
	s_waitcnt lgkmcnt(0)
; __device__ __forceinline__ void finishSM(f32x16& p0, f32x16& p1, float alpha, float& l_reg, bf16x8& pa0, bf16x8& pa1, bf16x8& pa2, bf16x8& pa3) {
; #pragma unroll
;     for (int r = 0; r < 16; ++r) p1[r] = __builtin_amdgcn_exp2f(p1[r]);
;     float ps = 0;
; #pragma unroll
;     for (int r = 0; r < 16; ++r) ps += p0[r];
; #pragma unroll
;     for (int r = 0; r < 16; ++r) ps += p1[r];
;     { auto rr = __builtin_amdgcn_permlane32_swap(__float_as_uint(ps), __float_as_uint(ps), false, false);
;       ps = __uint_as_float(rr[0]) + __uint_as_float(rr[1]); }
;     l_reg = l_reg * alpha + ps;
;     ...
;     PK4(p0, 0, pa0); PK4(p0, 8, pa1); PK4(p1, 0, pa2); PK4(p1, 8, pa3);
;     ...
; }
; __device__ __forceinline__ void qkt(f32x16& p0, f32x16& p1, const char* Kn, const bf16x8* qr, int r32, int hi) {
;     const char* Kr = Kn + KR_OFF;
;     p0 = f32x16{}; p1 = f32x16{};
;     __builtin_amdgcn_s_setprio(1);
; #pragma unroll
;     for (int d0 = 0; d0 < 8; ++d0) { const int cb = (d0 * 16 + hi * 8) * 2;
;         const bf16x8 b0 = *reinterpret_cast<const bf16x8*>(Kn + KNSWZ(r32, cb));
;         const bf16x8 b1 = *reinterpret_cast<const bf16x8*>(Kn + KNSWZ(32 + r32, cb));
;         p0 = __builtin_amdgcn_mfma_f32_32x32x16_bf16(b0, qr[d0], p0, 0, 0, 0);
;         p1 = __builtin_amdgcn_mfma_f32_32x32x16_bf16(b1, qr[d0], p1, 0, 0, 0); }
; #pragma unroll
;     for (int d0 = 0; d0 < 4; ++d0) { const int cb = (d0 * 16 + hi * 8) * 2;
;         const bf16x8 b0 = *reinterpret_cast<const bf16x8*>(Kr + KRSWZ(r32, cb));
;         const bf16x8 b1 = *reinterpret_cast<const bf16x8*>(Kr + KRSWZ(32 + r32, cb));
;         p0 = __builtin_amdgcn_mfma_f32_32x32x16_bf16(b0, qr[8 + d0], p0, 0, 0, 0);
;         p1 = __builtin_amdgcn_mfma_f32_32x32x16_bf16(b1, qr[8 + d0], p1, 0, 0, 0); }
; }
	v_mfma_f32_32x32x16_bf16 v[96:111], v[168:171], v[136:139], v[96:111]
	v_mfma_f32_32x32x16_bf16 v[64:79], v[186:189], v[136:139], v[64:79]
	v_add_u32_e32 v186, s14, v224
	ds_read_b128 v[168:171], v186
	ds_read_b128 v[186:189], v186 offset:8192
	s_mov_b32 m0, s15
	s_add_u32 s100, s72, 0x26580100
	s_addc_u32 s101, s73, 0
	global_load_lds_dwordx4 v176, s[100:101]
	v_exp_f32_e32 v192, v90
	s_waitcnt lgkmcnt(0)
	v_mfma_f32_32x32x16_bf16 v[96:111], v[168:171], v[132:135], v[96:111]
	v_mfma_f32_32x32x16_bf16 v[64:79], v[186:189], v[132:135], v[64:79]
	v_add_u32_e32 v186, s14, v225
	ds_read_b128 v[168:171], v186
	ds_read_b128 v[186:189], v186 offset:8192
	v_exp_f32_e32 v193, v91
	s_waitcnt lgkmcnt(0)
	v_mfma_f32_32x32x16_bf16 v[96:111], v[168:171], v[128:131], v[96:111]
	v_mfma_f32_32x32x16_bf16 v[64:79], v[186:189], v[128:131], v[64:79]
	v_add_u32_e32 v186, s14, v226
	ds_read_b128 v[168:171], v186 offset:16384
	ds_read_b128 v[186:189], v186 offset:20480
	s_add_i32 m0, s15, 0x400
	s_add_u32 s100, s72, 0x26580180
	s_addc_u32 s101, s73, 0
	global_load_lds_dwordx4 v176, s[100:101]
	v_exp_f32_e32 v241, v92
	s_waitcnt lgkmcnt(0)
	v_mfma_f32_32x32x16_bf16 v[96:111], v[168:171], v[124:127], v[96:111]
	v_mfma_f32_32x32x16_bf16 v[64:79], v[186:189], v[124:127], v[64:79]
	v_add_u32_e32 v186, s14, v227
	ds_read_b128 v[168:171], v186 offset:16384
	ds_read_b128 v[186:189], v186 offset:20480
	v_exp_f32_e32 v242, v93
	s_waitcnt lgkmcnt(0)
	v_mfma_f32_32x32x16_bf16 v[96:111], v[168:171], v[120:123], v[96:111]
	v_mfma_f32_32x32x16_bf16 v[64:79], v[186:189], v[120:123], v[64:79]
	v_add_u32_e32 v186, s14, v228
	ds_read_b128 v[168:171], v186 offset:16384
	ds_read_b128 v[186:189], v186 offset:20480
	s_add_i32 m0, s18, 0x4000
	s_add_u32 s100, s72, 0x21206000
	s_addc_u32 s101, s73, 0
	global_load_lds_dwordx4 v174, s[100:101]
	v_exp_f32_e32 v94, v94
	s_waitcnt lgkmcnt(0)
	v_mfma_f32_32x32x16_bf16 v[96:111], v[168:171], v[116:119], v[96:111]
	v_mfma_f32_32x32x16_bf16 v[64:79], v[186:189], v[116:119], v[64:79]
	v_add_u32_e32 v186, s14, v229
	ds_read_b128 v[168:171], v186 offset:16384
	ds_read_b128 v[186:189], v186 offset:20480
	v_exp_f32_e32 v95, v95
	s_waitcnt lgkmcnt(0)
	v_mfma_f32_32x32x16_bf16 v[96:111], v[168:171], v[112:115], v[96:111]
	v_exp_f32_e32 v168, v80
	v_add_f32_e32 v80, 0, v172
	v_add_f32_e32 v80, v173, v80
	v_add_f32_e32 v80, v182, v80
	v_add_f32_e32 v80, v195, v80
	v_add_f32_e32 v80, v196, v80
	v_add_f32_e32 v80, v197, v80
	v_add_f32_e32 v80, v198, v80
	v_add_f32_e32 v80, v199, v80
	v_add_f32_e32 v80, v200, v80
	v_add_f32_e32 v80, v234, v80
	v_add_f32_e32 v80, v235, v80
	v_add_f32_e32 v80, v236, v80
	v_add_f32_e32 v80, v237, v80
	v_exp_f32_e32 v169, v81
	v_add_f32_e32 v80, v238, v80
	v_exp_f32_e32 v170, v82
	v_add_f32_e32 v80, v239, v80
	v_exp_f32_e32 v171, v83
	v_add_f32_e32 v80, v240, v80
	v_mfma_f32_32x32x16_bf16 v[64:79], v[186:189], v[112:115], v[64:79]
	v_exp_f32_e32 v186, v84
	v_add_f32_e32 v80, v168, v80
	v_exp_f32_e32 v187, v85
	v_add_f32_e32 v80, v169, v80
	v_exp_f32_e32 v188, v86
	v_add_f32_e32 v80, v170, v80
	v_exp_f32_e32 v189, v87
	v_add_f32_e32 v80, v171, v80
	v_add_f32_e32 v80, v186, v80
	v_add_f32_e32 v80, v187, v80
	v_add_f32_e32 v80, v188, v80
	v_add_f32_e32 v80, v189, v80
	v_add_f32_e32 v80, v190, v80
	v_add_f32_e32 v80, v191, v80
	v_add_f32_e32 v80, v192, v80
	v_add_f32_e32 v80, v193, v80
	v_add_f32_e32 v80, v241, v80
	v_add_f32_e32 v80, v242, v80
	v_add_f32_e32 v80, v94, v80
	v_add_f32_e32 v80, v95, v80
	v_mov_b32_e32 v81, v80
	v_cvt_pk_bf16_f32 v82, v172, v173
	v_cvt_pk_bf16_f32 v83, v182, v195
	v_cvt_pk_bf16_f32 v84, v196, v197
	s_nop 1
	v_permlane32_swap_b32_e32 v80, v81
	v_cvt_pk_bf16_f32 v85, v198, v199
	v_permlane32_swap_b32_e32 v82, v84
	v_cvt_pk_bf16_f32 v86, v200, v234
	v_cvt_pk_bf16_f32 v87, v235, v236
	v_cvt_pk_bf16_f32 v88, v237, v238
	v_cvt_pk_bf16_f32 v89, v239, v240
	v_cvt_pk_bf16_f32 v90, v168, v169
	v_cvt_pk_bf16_f32 v91, v170, v171
	v_cvt_pk_bf16_f32 v92, v186, v187
	v_cvt_pk_bf16_f32 v93, v188, v189
	v_cvt_pk_bf16_f32 v168, v190, v191
	v_cvt_pk_bf16_f32 v169, v192, v193
	v_cvt_pk_bf16_f32 v170, v241, v242
	v_cvt_pk_bf16_f32 v171, v94, v95
	v_lshl_add_u32 v94, s13, 14, v205
	ds_read_b64_tr_b16 v[186:187], v94 offset:0
	ds_read_b64_tr_b16 v[188:189], v94 offset:0x800
	ds_read_b64_tr_b16 v[190:191], v94 offset:0x1000
	ds_read_b64_tr_b16 v[192:193], v94 offset:0x1800
	ds_read_b64_tr_b16 v[196:197], v94 offset:0x2000
	ds_read_b64_tr_b16 v[198:199], v94 offset:0x2800
	ds_read_b64_tr_b16 v[234:235], v94 offset:0x3000
	ds_read_b64_tr_b16 v[236:237], v94 offset:0x3800
	v_permlane32_swap_b32_e32 v83, v85
	v_permlane32_swap_b32_e32 v86, v88
	v_permlane32_swap_b32_e32 v87, v89
	v_permlane32_swap_b32_e32 v90, v92
	v_permlane32_swap_b32_e32 v91, v93
	v_permlane32_swap_b32_e32 v168, v170
	v_permlane32_swap_b32_e32 v169, v171
	s_waitcnt lgkmcnt(0)
; #define SBAR() __builtin_amdgcn_sched_barrier(0)
; template <bool FIRST>
; __device__ __forceinline__ void partialSM(f32x16& p0, f32x16& p1, float& m_reg, float& mn, float& alpha) {
;     float pmax = p0[0];
; #pragma unroll
;     for (int r = 1; r < 16; ++r) pmax = fmaxf(pmax, p0[r]);
; #pragma unroll
;     for (int r = 0; r < 16; ++r) pmax = fmaxf(pmax, p1[r]);
;     { auto rr = __builtin_amdgcn_permlane32_swap(__float_as_uint(pmax), __float_as_uint(pmax), false, false);
;       pmax = fmaxf(__uint_as_float(rr[0]), __uint_as_float(rr[1])); }
;     if (FIRST) { mn = (fabsf(pmax) <= THRL) ? 0.f : pmax; m_reg = mn; alpha = 1.f; }
;     else if (__builtin_expect(__all(pmax - m_reg <= THRL), 1)) { mn = m_reg; alpha = 1.f; }
;     else { mn = fmaxf(m_reg, pmax); alpha = __builtin_amdgcn_exp2f(m_reg - mn); m_reg = mn; }
; template <int OFF> __device__ __forceinline__ s16x4 tr_read(int vb) {
;     s16x4 r; asm volatile("ds_read_b64_tr_b16 %0, %1 offset:%2" : "=&v"(r) : "v"(vb), "i"(OFF) : "memory"); return r;
; }
; template <int D0> __device__ __forceinline__ void pv_one(f32x16& od, int vb, bf16x8 pa0, bf16x8 pa1, bf16x8 pa2, bf16x8 pa3) {
;     const s16x4 l0 = tr_read<v_rd_off(D0, 0, 0)>(vb), h0 = tr_read<v_rd_off(D0, 0, 1)>(vb), l1 = tr_read<v_rd_off(D0, 1, 0)>(vb), h1 = tr_read<v_rd_off(D0, 1, 1)>(vb);
;     const s16x4 l2 = tr_read<v_rd_off(D0, 2, 0)>(vb), h2 = tr_read<v_rd_off(D0, 2, 1)>(vb), l3 = tr_read<v_rd_off(D0, 3, 0)>(vb), h3 = tr_read<v_rd_off(D0, 3, 1)>(vb);
;     asm volatile("s_waitcnt lgkmcnt(0)" ::: "memory"); SBAR();
;     ...
;     od = __builtin_amdgcn_mfma_f32_32x32x16_bf16(pa0, PK(l0, h0), od, 0, 0, 0);
;     od = __builtin_amdgcn_mfma_f32_32x32x16_bf16(pa1, PK(l1, h1), od, 0, 0, 0);
;     od = __builtin_amdgcn_mfma_f32_32x32x16_bf16(pa2, PK(l2, h2), od, 0, 0, 0);
;     od = __builtin_amdgcn_mfma_f32_32x32x16_bf16(pa3, PK(l3, h3), od, 0, 0, 0);
;     ...
; }
; __device__ __forceinline__ void pv_d0(f32x16* o, int vb, bf16x8 pa0, bf16x8 pa1, bf16x8 pa2, bf16x8 pa3) {
;     pv_one<0>(o[0], vb, pa0, pa1, pa2, pa3); pv_one<1>(o[1], vb, pa0, pa1, pa2, pa3); pv_one<2>(o[2], vb, pa0, pa1, pa2, pa3); pv_one<3>(o[3], vb, pa0, pa1, pa2, pa3);
	s_nop 0
	v_mfma_f32_32x32x16_bf16 v[0:15], v[82:85], v[186:189], v[0:15]
	ds_read_b64_tr_b16 v[186:187], v94 offset:0x200
	ds_read_b64_tr_b16 v[188:189], v94 offset:0xa00
	v_mfma_f32_32x32x16_bf16 v[0:15], v[86:89], v[190:193], v[0:15]
	ds_read_b64_tr_b16 v[190:191], v94 offset:0x1200
	ds_read_b64_tr_b16 v[192:193], v94 offset:0x1a00
	v_mfma_f32_32x32x16_bf16 v[0:15], v[90:93], v[196:199], v[0:15]
	ds_read_b64_tr_b16 v[196:197], v94 offset:0x2200
	ds_read_b64_tr_b16 v[198:199], v94 offset:0x2a00
	v_mfma_f32_32x32x16_bf16 v[0:15], v[168:171], v[234:237], v[0:15]
	ds_read_b64_tr_b16 v[234:235], v94 offset:0x3200
	ds_read_b64_tr_b16 v[236:237], v94 offset:0x3a00
	s_waitcnt lgkmcnt(0)
	v_mfma_f32_32x32x16_bf16 v[48:63], v[82:85], v[186:189], v[48:63]
	ds_read_b64_tr_b16 v[186:187], v94 offset:0x400
	ds_read_b64_tr_b16 v[188:189], v94 offset:0xc00
	v_mfma_f32_32x32x16_bf16 v[48:63], v[86:89], v[190:193], v[48:63]
	ds_read_b64_tr_b16 v[190:191], v94 offset:0x1400
	ds_read_b64_tr_b16 v[192:193], v94 offset:0x1c00
	v_mfma_f32_32x32x16_bf16 v[48:63], v[90:93], v[196:199], v[48:63]
	ds_read_b64_tr_b16 v[196:197], v94 offset:0x2400
	ds_read_b64_tr_b16 v[198:199], v94 offset:0x2c00
	v_mfma_f32_32x32x16_bf16 v[48:63], v[168:171], v[234:237], v[48:63]
	ds_read_b64_tr_b16 v[234:235], v94 offset:0x3400
	ds_read_b64_tr_b16 v[236:237], v94 offset:0x3c00
	s_waitcnt lgkmcnt(0)
	v_mfma_f32_32x32x16_bf16 v[32:47], v[82:85], v[186:189], v[32:47]
	ds_read_b64_tr_b16 v[186:187], v94 offset:0x600
	ds_read_b64_tr_b16 v[188:189], v94 offset:0xe00
	v_mfma_f32_32x32x16_bf16 v[32:47], v[86:89], v[190:193], v[32:47]
	ds_read_b64_tr_b16 v[190:191], v94 offset:0x1600
	ds_read_b64_tr_b16 v[192:193], v94 offset:0x1e00
	v_mfma_f32_32x32x16_bf16 v[32:47], v[90:93], v[196:199], v[32:47]
	ds_read_b64_tr_b16 v[196:197], v94 offset:0x2600
	ds_read_b64_tr_b16 v[198:199], v94 offset:0x2e00
	v_mfma_f32_32x32x16_bf16 v[32:47], v[168:171], v[234:237], v[32:47]
	ds_read_b64_tr_b16 v[234:235], v94 offset:0x3600
	ds_read_b64_tr_b16 v[236:237], v94 offset:0x3e00
	s_waitcnt lgkmcnt(0)
	v_mfma_f32_32x32x16_bf16 v[16:31], v[82:85], v[186:189], v[16:31]
	v_max_f32_e32 v82, v97, v97
	v_max_f32_e32 v83, v96, v96
	v_max_f32_e32 v82, v83, v82
	v_max3_f32 v82, v82, v98, v99
	v_max3_f32 v82, v82, v100, v101
	v_max3_f32 v82, v82, v102, v103
	v_max3_f32 v82, v82, v104, v105
	v_mfma_f32_32x32x16_bf16 v[16:31], v[86:89], v[190:193], v[16:31]
	v_max3_f32 v82, v82, v106, v107
	v_max3_f32 v82, v82, v108, v109
	v_max3_f32 v82, v82, v110, v111
	v_max3_f32 v82, v82, v64, v65
	v_max3_f32 v82, v82, v66, v67
	v_max3_f32 v82, v82, v68, v69
	v_max3_f32 v82, v82, v70, v71
	v_mfma_f32_32x32x16_bf16 v[16:31], v[90:93], v[196:199], v[16:31]
	v_max3_f32 v82, v82, v72, v73
	v_max3_f32 v82, v82, v74, v75
	v_max3_f32 v82, v82, v76, v77
	v_max3_f32 v82, v82, v78, v79
	v_mov_b32_e32 v83, v82
	s_nop 1
	v_permlane32_swap_b32_e32 v82, v83
	v_max_f32_e32 v83, v83, v83
	v_max_f32_e32 v82, v82, v82
	v_mfma_f32_32x32x16_bf16 v[16:31], v[168:171], v[234:237], v[16:31]
	v_max_f32_e32 v82, v82, v83
	v_sub_f32_e32 v83, v82, v184
	s_mov_b32 s0, 0x41300000
	v_cmp_ge_f32_e32 vcc, s0, v83
	v_mov_b32_e32 v182, v184
	s_cmp_eq_u64 vcc, exec
	s_cbranch_scc0 .Latt_slow2
	s_cmp_lg_u32 s19, 0
	s_cbranch_scc0 .LBB0_229
	v_mov_b32_e32 v184, 1.0
